# v15
# baseline (speedup 1.0000x reference)
; __global__ void __launch_bounds__(512) mega(Params p_in, int pb, int pe) {
;     ...
;       const int i = (ph - 1) / 5, r5 = (ph - 1) % 5, j = i >> 1;
;       const bool ssd = (i & 1) == 0;
;       const int s = (r5 == 0) ? 0 : r5 + 1;
;       float* X = p.out;
;       float* sq_mix = p.ssq + (long)(2 * i) * TT * 8;
;       float* sq_mlp = p.ssq + (long)(2 * i + 1) * TT * 8;
;       float* sq_next = (i < 3) ? p.ssq + (long)(2 * i + 2) * TT * 8 : nullptr;
;       if (s == 0) { for (int rep = 0; rep < REP_G; ++rep) {
;         if (ssd) gemm_phase<EPI_INPROJ>(p.w_in + (long)j * NINP_PAD * DM, p.hn, DM, NINP_PAD, p.zx, ZXLD, p.dtraw, smem, sq_mix, nullptr);
;         else gemm_phase<EPI_QKV>(p.w_qkv + (long)j * 3 * DM * DM, p.hn, DM, 3 * DM, p.zx, 3 * DM, nullptr, smem, sq_mix, nullptr, 0, nullptr, &p, j); }
;       } else if (s == 1) { for (int rep = 0; rep < REP_E; ++rep) { if (ssd) conv_phase(p, j); else qknorm_phase(p, j); } }
;       else if (s == 2) { for (int rep = 0; rep < REP_M; ++rep) { if (ssd) ssd_phase(p, j, smem); else attn_phase(p, j, smem); } }
;       else if (s == 3) {
;         if (ssd) gemm_phase<EPI_RESID>(p.w_out + (long)j * DM * DIN, p.yn, DIN, DM, p.hn, 0, X, smem, nullptr, sq_mlp, 2, p.cnt + (2 * i) * 8);
;         else gemm_phase<EPI_RESID>(p.w_sbo + (long)j * DM * DM, p.yn, DM, DM, p.hn, 0, X, smem, nullptr, sq_mlp, 2, p.cnt + (2 * i) * 8);
;       } else if (s == 4) { for (int rep = 0; rep < REP_G; ++rep) gemm_phase<EPI_SQRELU>(p.w_up + (long)i * DFF * DM, p.hn, DM, DFF, p.u, DFF, nullptr, smem, sq_mlp, nullptr); }
;       else gemm_phase<EPI_RESID>(p.w_down + (long)i * DM * DFF, p.u, DFF, DM, p.hn, 0, X, smem, nullptr, sq_next, 4, p.cnt + (2 * i + 1) * 8);
.LBB0_6:
	s_mov_b32 s98, 0x108420
	s_bitcmp1_b32 s98, s88
	s_cbranch_scc0 .Lmy_xstag_done
	s_cmp_lt_u32 s2, 32
	s_cbranch_scc1 .Lmy_xstag_done
	s_and_b32 s98, s2, 7
.Lmy_xstag_loop:
	s_cmp_eq_u32 s98, 0
	s_cbranch_scc1 .Lmy_xstag_done
	s_sleep 48
	s_sub_u32 s98, s98, 1
	s_branch .Lmy_xstag_loop
